# attention near-diagonal tiles: first four bias-table reads issued ahead of the QK MFMAs
# baseline (speedup 1.0000x reference)
.LBB0_185:
	ds_read_b128 v[126:129], v244 offset:16384
	s_waitcnt lgkmcnt(1)
	v_mfma_f32_32x32x16_bf16 v[82:97], v[202:205], v[146:149], v[66:81]
	s_add_i32 s22, s21, 64
	s_cmp_le_u32 s22, s20
	s_cbranch_scc0 .Lnpre0
.Lnret0:
	ds_read_b128 v[122:125], v240 offset:24576
	v_mfma_f32_32x32x16_bf16 v[98:113], v[194:197], v[146:149], v[66:81]
	ds_read_b128 v[114:117], v241 offset:16384
	v_mfma_f32_32x32x16_bf16 v[82:97], v[198:201], v[150:153], v[82:97]
	ds_read_b128 v[118:121], v241 offset:24576
	s_waitcnt lgkmcnt(0)
	v_mfma_f32_32x32x16_bf16 v[98:113], v[122:125], v[150:153], v[98:113]
	ds_read_b128 v[122:125], v243 offset:16384
	v_mfma_f32_32x32x16_bf16 v[82:97], v[114:117], v[154:157], v[82:97]
	ds_read_b128 v[114:117], v243 offset:24576
	v_mfma_f32_32x32x16_bf16 v[98:113], v[118:121], v[154:157], v[98:113]
	s_waitcnt lgkmcnt(0)
	v_mfma_f32_32x32x16_bf16 v[82:97], v[122:125], v[158:161], v[82:97]
	v_mfma_f32_32x32x16_bf16 v[98:113], v[114:117], v[158:161], v[98:113]
	s_nop 0
	ds_read_b128 v[122:125], v244 offset:20480
	ds_read_b128 v[118:121], v244 offset:24576
	ds_read_b128 v[114:117], v244 offset:28672
	s_add_i32 s22, s21, 64
	s_cmp_le_u32 s22, s20
	s_cbranch_scc0 .Lnear_u1e

.LBB0_225:
	ds_read_b128 v[126:129], v244 offset:32768
	s_waitcnt lgkmcnt(1)
	v_mfma_f32_32x32x16_bf16 v[82:97], v[202:205], v[146:149], v[66:81]
	s_add_i32 s26, s21, 0x80
	s_cmp_le_u32 s26, s20
	s_cbranch_scc0 .Lnpre1
.Lnret1:
	ds_read_b128 v[122:125], v240 offset:40960
	v_mfma_f32_32x32x16_bf16 v[98:113], v[194:197], v[146:149], v[66:81]
	ds_read_b128 v[114:117], v241 offset:32768
	v_mfma_f32_32x32x16_bf16 v[82:97], v[198:201], v[150:153], v[82:97]
	ds_read_b128 v[118:121], v241 offset:40960
	s_waitcnt lgkmcnt(0)
	v_mfma_f32_32x32x16_bf16 v[98:113], v[122:125], v[150:153], v[98:113]
	ds_read_b128 v[122:125], v243 offset:32768
	v_mfma_f32_32x32x16_bf16 v[82:97], v[114:117], v[154:157], v[82:97]
	ds_read_b128 v[114:117], v243 offset:40960
	v_mfma_f32_32x32x16_bf16 v[98:113], v[118:121], v[154:157], v[98:113]
	s_waitcnt lgkmcnt(0)
	v_mfma_f32_32x32x16_bf16 v[82:97], v[122:125], v[158:161], v[82:97]
	v_mfma_f32_32x32x16_bf16 v[98:113], v[114:117], v[158:161], v[98:113]
	s_nop 0
	ds_read_b128 v[122:125], v244 offset:36864
	ds_read_b128 v[118:121], v244 offset:40960
	ds_read_b128 v[114:117], v244 offset:45056
	s_add_i32 s26, s21, 0x80
	s_cmp_le_u32 s26, s20
	s_cbranch_scc0 .Lnear_u1o

.Lnpre0:
	v_add_u32_e32 v130, s21, v248
	v_add_u32_e32 v130, 0x11f, v130
	v_and_b32_e32 v130, 0x3ffffffc, v130
	v_lshl_add_u32 v166, v130, 2, v0
	ds_read_b128 v[130:133], v166
	ds_read_b128 v[134:137], v166 offset:16
	ds_read_b128 v[138:141], v166 offset:64
	ds_read_b128 v[142:145], v166 offset:80
	s_branch .Lnret0
.Lnear_u1e:
	s_waitcnt lgkmcnt(0)
	v_add_f32_e32 v84, v84, v132
	v_add_f32_e32 v85, v85, v133
	v_add_f32_e32 v86, v86, v134
	v_add_f32_e32 v87, v87, v135
	v_add_f32_e32 v90, v90, v138
	v_add_f32_e32 v91, v91, v139
	v_add_f32_e32 v94, v94, v142
	v_add_f32_e32 v95, v95, v143
	v_add_f32_e32 v96, v96, v144
	v_add_f32_e32 v97, v97, v145
	v_add_f32_e32 v92, v92, v140
	v_add_f32_e32 v93, v93, v141
	v_add_f32_e32 v88, v88, v136
	v_add_f32_e32 v89, v89, v137
	v_add_f32_e32 v82, v82, v130
	v_add_f32_e32 v83, v83, v131
	ds_read_b128 v[130:133], v166 offset:128
	ds_read_b128 v[134:137], v166 offset:144
	ds_read_b128 v[138:141], v166 offset:192
	ds_read_b128 v[142:145], v166 offset:208
	s_waitcnt lgkmcnt(0)
	v_add_f32_e32 v100, v100, v132
	v_add_f32_e32 v101, v101, v133
	v_add_f32_e32 v102, v102, v134
	v_add_f32_e32 v103, v103, v135
	v_add_f32_e32 v106, v106, v138
	v_add_f32_e32 v107, v107, v139
	v_add_f32_e32 v110, v110, v142
	v_add_f32_e32 v111, v111, v143
	v_add_f32_e32 v112, v112, v144
	v_add_f32_e32 v113, v113, v145
	v_add_f32_e32 v108, v108, v140
	v_add_f32_e32 v109, v109, v141
	v_add_f32_e32 v104, v104, v136
	v_add_f32_e32 v105, v105, v137
	v_add_f32_e32 v98, v98, v130
	v_add_f32_e32 v99, v99, v131
	s_branch .LBB0_188
.Lnpre1:
	v_add_u32_e32 v130, s21, v248
	v_add_u32_e32 v130, 0x15f, v130
	v_and_b32_e32 v130, 0x3ffffffc, v130
	v_lshl_add_u32 v162, v130, 2, v0
	ds_read_b128 v[130:133], v162
	ds_read_b128 v[134:137], v162 offset:16
	ds_read_b128 v[138:141], v162 offset:64
	ds_read_b128 v[142:145], v162 offset:80
	s_branch .Lnret1
.Lnear_u1o:
	s_waitcnt lgkmcnt(0)
	v_add_f32_e32 v84, v84, v132
	v_add_f32_e32 v85, v85, v133
	v_add_f32_e32 v86, v86, v134
	v_add_f32_e32 v87, v87, v135
	v_add_f32_e32 v90, v90, v138
	v_add_f32_e32 v91, v91, v139
	v_add_f32_e32 v94, v94, v142
	v_add_f32_e32 v95, v95, v143
	v_add_f32_e32 v96, v96, v144
	v_add_f32_e32 v97, v97, v145
	v_add_f32_e32 v92, v92, v140
	v_add_f32_e32 v93, v93, v141
	v_add_f32_e32 v88, v88, v136
	v_add_f32_e32 v89, v89, v137
	v_add_f32_e32 v82, v82, v130
	v_add_f32_e32 v83, v83, v131
	ds_read_b128 v[130:133], v162 offset:128
	ds_read_b128 v[134:137], v162 offset:144
	ds_read_b128 v[138:141], v162 offset:192
	ds_read_b128 v[142:145], v162 offset:208
	s_waitcnt lgkmcnt(0)
	v_add_f32_e32 v100, v100, v132
	v_add_f32_e32 v101, v101, v133
	v_add_f32_e32 v102, v102, v134
	v_add_f32_e32 v103, v103, v135
	v_add_f32_e32 v106, v106, v138
	v_add_f32_e32 v107, v107, v139
	v_add_f32_e32 v110, v110, v142
	v_add_f32_e32 v111, v111, v143
	v_add_f32_e32 v112, v112, v144
	v_add_f32_e32 v113, v113, v145
	v_add_f32_e32 v108, v108, v140
	v_add_f32_e32 v109, v109, v141
	v_add_f32_e32 v104, v104, v136
	v_add_f32_e32 v105, v105, v137
	v_add_f32_e32 v98, v98, v130
	v_add_f32_e32 v99, v99, v131
	s_branch .LBB0_228

.Lr1u1_LBB0_185:
	ds_read_b128 v[126:129], v244 offset:49152
	s_waitcnt lgkmcnt(1)
	v_mfma_f32_32x32x16_bf16 v[82:97], v[202:205], v[146:149], v[66:81]
	s_add_i32 s22, s21, 64
	s_cmp_le_u32 s22, s20
	s_cbranch_scc0 .Lnpre2
.Lnret2:
	ds_read_b128 v[122:125], v240 offset:8192
	v_mfma_f32_32x32x16_bf16 v[98:113], v[194:197], v[146:149], v[66:81]
	ds_read_b128 v[114:117], v241
	v_mfma_f32_32x32x16_bf16 v[82:97], v[198:201], v[150:153], v[82:97]
	ds_read_b128 v[118:121], v241 offset:8192
	s_waitcnt lgkmcnt(0)
	v_mfma_f32_32x32x16_bf16 v[98:113], v[122:125], v[150:153], v[98:113]
	ds_read_b128 v[122:125], v243
	v_mfma_f32_32x32x16_bf16 v[82:97], v[114:117], v[154:157], v[82:97]
	ds_read_b128 v[114:117], v243 offset:8192
	v_mfma_f32_32x32x16_bf16 v[98:113], v[118:121], v[154:157], v[98:113]
	s_waitcnt lgkmcnt(0)
	v_mfma_f32_32x32x16_bf16 v[82:97], v[122:125], v[158:161], v[82:97]
	v_mfma_f32_32x32x16_bf16 v[98:113], v[114:117], v[158:161], v[98:113]
	s_nop 0
	ds_read_b128 v[122:125], v244 offset:53248
	ds_read_b128 v[118:121], v244 offset:57344
	ds_read_b128 v[114:117], v244 offset:61440
	s_add_i32 s22, s21, 64
	s_cmp_le_u32 s22, s20
	s_cbranch_scc0 .Lr1u1_Lnear_u1e

.Lr1u1_LBB0_225:
	ds_read_b128 v[126:129], v244 offset:16384
	s_waitcnt lgkmcnt(1)
	v_mfma_f32_32x32x16_bf16 v[82:97], v[202:205], v[146:149], v[66:81]
	s_add_i32 s26, s21, 0x80
	s_cmp_le_u32 s26, s20
	s_cbranch_scc0 .Lnpre3
.Lnret3:
	ds_read_b128 v[122:125], v240 offset:24576
	v_mfma_f32_32x32x16_bf16 v[98:113], v[194:197], v[146:149], v[66:81]
	ds_read_b128 v[114:117], v241 offset:16384
	v_mfma_f32_32x32x16_bf16 v[82:97], v[198:201], v[150:153], v[82:97]
	ds_read_b128 v[118:121], v241 offset:24576
	s_waitcnt lgkmcnt(0)
	v_mfma_f32_32x32x16_bf16 v[98:113], v[122:125], v[150:153], v[98:113]
	ds_read_b128 v[122:125], v243 offset:16384
	v_mfma_f32_32x32x16_bf16 v[82:97], v[114:117], v[154:157], v[82:97]
	ds_read_b128 v[114:117], v243 offset:24576
	v_mfma_f32_32x32x16_bf16 v[98:113], v[118:121], v[154:157], v[98:113]
	s_waitcnt lgkmcnt(0)
	v_mfma_f32_32x32x16_bf16 v[82:97], v[122:125], v[158:161], v[82:97]
	v_mfma_f32_32x32x16_bf16 v[98:113], v[114:117], v[158:161], v[98:113]
	s_nop 0
	ds_read_b128 v[122:125], v244 offset:20480
	ds_read_b128 v[118:121], v244 offset:24576
	ds_read_b128 v[114:117], v244 offset:28672
	s_add_i32 s26, s21, 0x80
	s_cmp_le_u32 s26, s20
	s_cbranch_scc0 .Lr1u1_Lnear_u1o

.Lr2u1_LBB0_185:
	ds_read_b128 v[126:129], v244 offset:32768
	s_waitcnt lgkmcnt(1)
	v_mfma_f32_32x32x16_bf16 v[82:97], v[202:205], v[146:149], v[66:81]
	s_add_i32 s22, s21, 64
	s_cmp_le_u32 s22, s20
	s_cbranch_scc0 .Lnpre4
.Lnret4:
	ds_read_b128 v[122:125], v240 offset:40960
	v_mfma_f32_32x32x16_bf16 v[98:113], v[194:197], v[146:149], v[66:81]
	ds_read_b128 v[114:117], v241 offset:32768
	v_mfma_f32_32x32x16_bf16 v[82:97], v[198:201], v[150:153], v[82:97]
	ds_read_b128 v[118:121], v241 offset:40960
	s_waitcnt lgkmcnt(0)
	v_mfma_f32_32x32x16_bf16 v[98:113], v[122:125], v[150:153], v[98:113]
	ds_read_b128 v[122:125], v243 offset:32768
	v_mfma_f32_32x32x16_bf16 v[82:97], v[114:117], v[154:157], v[82:97]
	ds_read_b128 v[114:117], v243 offset:40960
	v_mfma_f32_32x32x16_bf16 v[98:113], v[118:121], v[154:157], v[98:113]
	s_waitcnt lgkmcnt(0)
	v_mfma_f32_32x32x16_bf16 v[82:97], v[122:125], v[158:161], v[82:97]
	v_mfma_f32_32x32x16_bf16 v[98:113], v[114:117], v[158:161], v[98:113]
	s_nop 0
	ds_read_b128 v[122:125], v244 offset:36864
	ds_read_b128 v[118:121], v244 offset:40960
	ds_read_b128 v[114:117], v244 offset:45056
	s_add_i32 s22, s21, 64
	s_cmp_le_u32 s22, s20
	s_cbranch_scc0 .Lr2u1_Lnear_u1e

.Lr2u1_LBB0_225:
	ds_read_b128 v[126:129], v244 offset:49152
	s_waitcnt lgkmcnt(1)
	v_mfma_f32_32x32x16_bf16 v[82:97], v[202:205], v[146:149], v[66:81]
	s_add_i32 s26, s21, 0x80
	s_cmp_le_u32 s26, s20
	s_cbranch_scc0 .Lnpre5
.Lnret5:
	ds_read_b128 v[122:125], v240 offset:8192
	v_mfma_f32_32x32x16_bf16 v[98:113], v[194:197], v[146:149], v[66:81]
	ds_read_b128 v[114:117], v241
	v_mfma_f32_32x32x16_bf16 v[82:97], v[198:201], v[150:153], v[82:97]
	ds_read_b128 v[118:121], v241 offset:8192
	s_waitcnt lgkmcnt(0)
	v_mfma_f32_32x32x16_bf16 v[98:113], v[122:125], v[150:153], v[98:113]
	ds_read_b128 v[122:125], v243
	v_mfma_f32_32x32x16_bf16 v[82:97], v[114:117], v[154:157], v[82:97]
	ds_read_b128 v[114:117], v243 offset:8192
	v_mfma_f32_32x32x16_bf16 v[98:113], v[118:121], v[154:157], v[98:113]
	s_waitcnt lgkmcnt(0)
	v_mfma_f32_32x32x16_bf16 v[82:97], v[122:125], v[158:161], v[82:97]
	v_mfma_f32_32x32x16_bf16 v[98:113], v[114:117], v[158:161], v[98:113]
	s_nop 0
	ds_read_b128 v[122:125], v244 offset:53248
	ds_read_b128 v[118:121], v244 offset:57344
	ds_read_b128 v[114:117], v244 offset:61440
	s_add_i32 s26, s21, 0x80
	s_cmp_le_u32 s26, s20
	s_cbranch_scc0 .Lr2u1_Lnear_u1o

.LBB0_288:
	ds_read_b128 v[126:129], v245 offset:16384
	s_waitcnt lgkmcnt(1)
	v_mfma_f32_32x32x16_bf16 v[82:97], v[202:205], v[146:149], v[66:81]
	s_cmp_le_u32 s20, s16
	s_cbranch_scc0 .Lnpre6
.Lnret6:
	ds_read_b128 v[122:125], v240 offset:24576
	v_mfma_f32_32x32x16_bf16 v[98:113], v[194:197], v[146:149], v[66:81]
	ds_read_b128 v[114:117], v241 offset:16384
	v_mfma_f32_32x32x16_bf16 v[82:97], v[198:201], v[150:153], v[82:97]
	ds_read_b128 v[118:121], v241 offset:24576
	s_waitcnt lgkmcnt(0)
	v_mfma_f32_32x32x16_bf16 v[98:113], v[122:125], v[150:153], v[98:113]
	ds_read_b128 v[122:125], v242 offset:16384
	v_mfma_f32_32x32x16_bf16 v[82:97], v[114:117], v[154:157], v[82:97]
	ds_read_b128 v[114:117], v242 offset:24576
	v_mfma_f32_32x32x16_bf16 v[98:113], v[118:121], v[154:157], v[98:113]
	s_waitcnt lgkmcnt(0)
	v_mfma_f32_32x32x16_bf16 v[82:97], v[122:125], v[158:161], v[82:97]
	v_mfma_f32_32x32x16_bf16 v[98:113], v[114:117], v[158:161], v[98:113]
	s_nop 0
	ds_read_b128 v[122:125], v245 offset:20480
	ds_read_b128 v[118:121], v245 offset:24576
	ds_read_b128 v[114:117], v245 offset:28672
	s_cmp_le_u32 s20, s16
	s_cbranch_scc0 .Lnear_u2e

.LBB0_328:
	ds_read_b128 v[126:129], v245 offset:32768
	s_waitcnt lgkmcnt(1)
	v_mfma_f32_32x32x16_bf16 v[82:97], v[202:205], v[146:149], v[66:81]
	s_add_i32 s26, s20, 64
	s_cmp_le_u32 s26, s16
	s_cbranch_scc0 .Lnpre7
.Lnret7:
	ds_read_b128 v[122:125], v240 offset:40960
	v_mfma_f32_32x32x16_bf16 v[98:113], v[194:197], v[146:149], v[66:81]
	ds_read_b128 v[114:117], v241 offset:32768
	v_mfma_f32_32x32x16_bf16 v[82:97], v[198:201], v[150:153], v[82:97]
	ds_read_b128 v[118:121], v241 offset:40960
	s_waitcnt lgkmcnt(0)
	v_mfma_f32_32x32x16_bf16 v[98:113], v[122:125], v[150:153], v[98:113]
	ds_read_b128 v[122:125], v242 offset:32768
	v_mfma_f32_32x32x16_bf16 v[82:97], v[114:117], v[154:157], v[82:97]
	ds_read_b128 v[114:117], v242 offset:40960
	v_mfma_f32_32x32x16_bf16 v[98:113], v[118:121], v[154:157], v[98:113]
	s_waitcnt lgkmcnt(0)
	v_mfma_f32_32x32x16_bf16 v[82:97], v[122:125], v[158:161], v[82:97]
	v_mfma_f32_32x32x16_bf16 v[98:113], v[114:117], v[158:161], v[98:113]
	s_nop 0
	ds_read_b128 v[122:125], v245 offset:36864
	ds_read_b128 v[118:121], v245 offset:40960
	ds_read_b128 v[114:117], v245 offset:45056
	s_add_i32 s26, s20, 64
	s_cmp_le_u32 s26, s16
	s_cbranch_scc0 .Lnear_u2o

.Lnpre6:
	v_add3_u32 v130, v249, s20, 47
	v_and_b32_e32 v130, 0x3ffffffc, v130
	v_lshl_add_u32 v166, v130, 2, v244
	ds_read_b128 v[130:133], v166
	ds_read_b128 v[134:137], v166 offset:16
	ds_read_b128 v[138:141], v166 offset:64
	ds_read_b128 v[142:145], v166 offset:80
	s_branch .Lnret6
.Lnear_u2e:
	s_waitcnt lgkmcnt(0)
	v_add_f32_e32 v84, v84, v132
	v_add_f32_e32 v85, v85, v133
	v_add_f32_e32 v88, v88, v136
	v_add_f32_e32 v89, v89, v137
	v_add_f32_e32 v92, v92, v140
	v_add_f32_e32 v93, v93, v141
	v_add_f32_e32 v96, v96, v144
	v_add_f32_e32 v97, v97, v145
	v_add_f32_e32 v94, v94, v142
	v_add_f32_e32 v95, v95, v143
	v_add_f32_e32 v90, v90, v138
	v_add_f32_e32 v91, v91, v139
	v_add_f32_e32 v86, v86, v134
	v_add_f32_e32 v87, v87, v135
	v_add_f32_e32 v82, v82, v130
	v_add_f32_e32 v83, v83, v131
	ds_read_b128 v[130:133], v166 offset:128
	ds_read_b128 v[134:137], v166 offset:144
	ds_read_b128 v[138:141], v166 offset:192
	ds_read_b128 v[142:145], v166 offset:208
	s_waitcnt lgkmcnt(0)
	v_add_f32_e32 v100, v100, v132
	v_add_f32_e32 v101, v101, v133
	v_add_f32_e32 v104, v104, v136
	v_add_f32_e32 v105, v105, v137
	v_add_f32_e32 v108, v108, v140
	v_add_f32_e32 v109, v109, v141
	v_add_f32_e32 v112, v112, v144
	v_add_f32_e32 v113, v113, v145
	v_add_f32_e32 v110, v110, v142
	v_add_f32_e32 v111, v111, v143
	v_add_f32_e32 v106, v106, v138
	v_add_f32_e32 v107, v107, v139
	v_add_f32_e32 v102, v102, v134
	v_add_f32_e32 v103, v103, v135
	v_add_f32_e32 v98, v98, v130
	v_add_f32_e32 v99, v99, v131
	s_branch .LBB0_291
.Lnpre7:
	v_add_u32_e32 v130, s20, v249
	v_add_u32_e32 v130, 0x6f, v130
	v_and_b32_e32 v130, 0x3ffffffc, v130
	v_lshl_add_u32 v162, v130, 2, v244
	ds_read_b128 v[130:133], v162
	ds_read_b128 v[134:137], v162 offset:16
	ds_read_b128 v[138:141], v162 offset:64
	ds_read_b128 v[142:145], v162 offset:80
	s_branch .Lnret7

.Lr1u2_LBB0_288:
	ds_read_b128 v[126:129], v245 offset:49152
	s_waitcnt lgkmcnt(1)
	v_mfma_f32_32x32x16_bf16 v[82:97], v[202:205], v[146:149], v[66:81]
	s_cmp_le_u32 s20, s16
	s_cbranch_scc0 .Lnpre8
.Lnret8:
	ds_read_b128 v[122:125], v240 offset:8192
	v_mfma_f32_32x32x16_bf16 v[98:113], v[194:197], v[146:149], v[66:81]
	ds_read_b128 v[114:117], v241
	v_mfma_f32_32x32x16_bf16 v[82:97], v[198:201], v[150:153], v[82:97]
	ds_read_b128 v[118:121], v241 offset:8192
	s_waitcnt lgkmcnt(0)
	v_mfma_f32_32x32x16_bf16 v[98:113], v[122:125], v[150:153], v[98:113]
	ds_read_b128 v[122:125], v242
	v_mfma_f32_32x32x16_bf16 v[82:97], v[114:117], v[154:157], v[82:97]
	ds_read_b128 v[114:117], v242 offset:8192
	v_mfma_f32_32x32x16_bf16 v[98:113], v[118:121], v[154:157], v[98:113]
	s_waitcnt lgkmcnt(0)
	v_mfma_f32_32x32x16_bf16 v[82:97], v[122:125], v[158:161], v[82:97]
	v_mfma_f32_32x32x16_bf16 v[98:113], v[114:117], v[158:161], v[98:113]
	s_nop 0
	ds_read_b128 v[122:125], v245 offset:53248
	ds_read_b128 v[118:121], v245 offset:57344
	ds_read_b128 v[114:117], v245 offset:61440
	s_cmp_le_u32 s20, s16
	s_cbranch_scc0 .Lr1u2_Lnear_u2e

.Lr1u2_LBB0_328:
	ds_read_b128 v[126:129], v245 offset:16384
	s_waitcnt lgkmcnt(1)
	v_mfma_f32_32x32x16_bf16 v[82:97], v[202:205], v[146:149], v[66:81]
	s_add_i32 s26, s20, 64
	s_cmp_le_u32 s26, s16
	s_cbranch_scc0 .Lnpre9
.Lnret9:
	ds_read_b128 v[122:125], v240 offset:24576
	v_mfma_f32_32x32x16_bf16 v[98:113], v[194:197], v[146:149], v[66:81]
	ds_read_b128 v[114:117], v241 offset:16384
	v_mfma_f32_32x32x16_bf16 v[82:97], v[198:201], v[150:153], v[82:97]
	ds_read_b128 v[118:121], v241 offset:24576
	s_waitcnt lgkmcnt(0)
	v_mfma_f32_32x32x16_bf16 v[98:113], v[122:125], v[150:153], v[98:113]
	ds_read_b128 v[122:125], v242 offset:16384
	v_mfma_f32_32x32x16_bf16 v[82:97], v[114:117], v[154:157], v[82:97]
	ds_read_b128 v[114:117], v242 offset:24576
	v_mfma_f32_32x32x16_bf16 v[98:113], v[118:121], v[154:157], v[98:113]
	s_waitcnt lgkmcnt(0)
	v_mfma_f32_32x32x16_bf16 v[82:97], v[122:125], v[158:161], v[82:97]
	v_mfma_f32_32x32x16_bf16 v[98:113], v[114:117], v[158:161], v[98:113]
	s_nop 0
	ds_read_b128 v[122:125], v245 offset:20480
	ds_read_b128 v[118:121], v245 offset:24576
	ds_read_b128 v[114:117], v245 offset:28672
	s_add_i32 s26, s20, 64
	s_cmp_le_u32 s26, s16
	s_cbranch_scc0 .Lr1u2_Lnear_u2o

.Lr2u2_LBB0_288:
	ds_read_b128 v[126:129], v245 offset:32768
	s_waitcnt lgkmcnt(1)
	v_mfma_f32_32x32x16_bf16 v[82:97], v[202:205], v[146:149], v[66:81]
	s_cmp_le_u32 s20, s16
	s_cbranch_scc0 .Lnpre10
.Lnret10:
	ds_read_b128 v[122:125], v240 offset:40960
	v_mfma_f32_32x32x16_bf16 v[98:113], v[194:197], v[146:149], v[66:81]
	ds_read_b128 v[114:117], v241 offset:32768
	v_mfma_f32_32x32x16_bf16 v[82:97], v[198:201], v[150:153], v[82:97]
	ds_read_b128 v[118:121], v241 offset:40960
	s_waitcnt lgkmcnt(0)
	v_mfma_f32_32x32x16_bf16 v[98:113], v[122:125], v[150:153], v[98:113]
	ds_read_b128 v[122:125], v242 offset:32768
	v_mfma_f32_32x32x16_bf16 v[82:97], v[114:117], v[154:157], v[82:97]
	ds_read_b128 v[114:117], v242 offset:40960
	v_mfma_f32_32x32x16_bf16 v[98:113], v[118:121], v[154:157], v[98:113]
	s_waitcnt lgkmcnt(0)
	v_mfma_f32_32x32x16_bf16 v[82:97], v[122:125], v[158:161], v[82:97]
	v_mfma_f32_32x32x16_bf16 v[98:113], v[114:117], v[158:161], v[98:113]
	s_nop 0
	ds_read_b128 v[122:125], v245 offset:36864
	ds_read_b128 v[118:121], v245 offset:40960
	ds_read_b128 v[114:117], v245 offset:45056
	s_cmp_le_u32 s20, s16
	s_cbranch_scc0 .Lr2u2_Lnear_u2e

.Lr2u2_LBB0_328:
	ds_read_b128 v[126:129], v245 offset:49152
	s_waitcnt lgkmcnt(1)
	v_mfma_f32_32x32x16_bf16 v[82:97], v[202:205], v[146:149], v[66:81]
	s_add_i32 s26, s20, 64
	s_cmp_le_u32 s26, s16
	s_cbranch_scc0 .Lnpre11
.Lnret11:
	ds_read_b128 v[122:125], v240 offset:8192
	v_mfma_f32_32x32x16_bf16 v[98:113], v[194:197], v[146:149], v[66:81]
	ds_read_b128 v[114:117], v241
	v_mfma_f32_32x32x16_bf16 v[82:97], v[198:201], v[150:153], v[82:97]
	ds_read_b128 v[118:121], v241 offset:8192
	s_waitcnt lgkmcnt(0)
	v_mfma_f32_32x32x16_bf16 v[98:113], v[122:125], v[150:153], v[98:113]
	ds_read_b128 v[122:125], v242
	v_mfma_f32_32x32x16_bf16 v[82:97], v[114:117], v[154:157], v[82:97]
	ds_read_b128 v[114:117], v242 offset:8192
	v_mfma_f32_32x32x16_bf16 v[98:113], v[118:121], v[154:157], v[98:113]
	s_waitcnt lgkmcnt(0)
	v_mfma_f32_32x32x16_bf16 v[82:97], v[122:125], v[158:161], v[82:97]
	v_mfma_f32_32x32x16_bf16 v[98:113], v[114:117], v[158:161], v[98:113]
	s_nop 0
	ds_read_b128 v[122:125], v245 offset:53248
	ds_read_b128 v[118:121], v245 offset:57344
	ds_read_b128 v[114:117], v245 offset:61440
	s_add_i32 s26, s20, 64
	s_cmp_le_u32 s26, s16
	s_cbranch_scc0 .Lr2u2_Lnear_u2o
